# attention output ladder: pairs of 8-byte row-per-lane stores exchanged across half-waves with v_permlane32_swap and written as 16-byte stores
# speedup vs baseline: 1.0166x; 1.0016x over previous
.Lpf_done:
	v_mov_b32_e32 v128, v197
	v_mov_b32_e32 v129, v196
	s_nop 0
	v_permlane32_swap_b32_e32 v197, v128
	v_permlane32_swap_b32_e32 v196, v129
	v_add_f32_e32 v148, v197, v128
	v_add_f32_e32 v149, v196, v129
	v_div_scale_f32 v150, s[0:1], v148, v148, 1.0
	v_div_scale_f32 v152, s[0:1], v149, v149, -v208
	v_rcp_f32_e32 v154, v150
	v_rcp_f32_e32 v155, v152
	v_div_scale_f32 v151, vcc, 1.0, v148, 1.0
	v_fma_f32 v156, -v150, v154, 1.0
	v_fma_f32 v157, -v152, v155, 1.0
	v_fmac_f32_e32 v154, v156, v154
	v_div_scale_f32 v153, s[36:37], -v208, v149, -v208
	v_fmac_f32_e32 v155, v157, v155
	v_mul_f32_e32 v156, v151, v154
	v_mul_f32_e32 v157, v153, v155
	v_fma_f32 v158, -v150, v156, v151
	v_fma_f32 v159, -v152, v157, v153
	v_fmac_f32_e32 v156, v158, v154
	v_fmac_f32_e32 v157, v159, v155
	v_fma_f32 v150, -v150, v156, v151
	v_fma_f32 v151, -v152, v157, v153
	v_div_fmas_f32 v150, v150, v154, v156
	s_mov_b64 vcc, s[36:37]
	v_div_fixup_f32 v148, v150, v148, 1.0
	v_div_fmas_f32 v150, v151, v155, v157
	v_div_fixup_f32 v150, v150, v149, -v208
	v_pk_mul_f32 v[96:97], v[96:97], v[150:151] op_sel_hi:[1,0]
	v_pk_mul_f32 v[98:99], v[98:99], v[150:151] op_sel_hi:[1,0]
	v_pk_fma_f32 v[112:113], v[112:113], v[148:149], v[96:97] op_sel_hi:[1,0,1]
	v_pk_fma_f32 v[114:115], v[114:115], v[148:149], v[98:99] op_sel_hi:[1,0,1]
	v_mul_f32_e32 v96, v113, v113
	v_pk_fma_f32 v[96:97], v[112:113], v[112:113], v[96:97] op_sel_hi:[1,1,0]
	v_pk_mul_f32 v[100:101], v[100:101], v[150:151] op_sel_hi:[1,0]
	v_mul_f32_e32 v98, v115, v115
	v_pk_fma_f32 v[96:97], v[114:115], v[114:115], v[96:97]
	v_pk_fma_f32 v[100:101], v[116:117], v[148:149], v[100:101] op_sel_hi:[1,0,1]
	v_pk_add_f32 v[96:97], v[98:99], v[96:97] op_sel_hi:[0,1]
	v_pk_mul_f32 v[102:103], v[102:103], v[150:151] op_sel_hi:[1,0]
	v_mul_f32_e32 v116, v101, v101
	v_pk_fma_f32 v[96:97], v[100:101], v[100:101], v[96:97]
	v_pk_fma_f32 v[102:103], v[118:119], v[148:149], v[102:103] op_sel_hi:[1,0,1]
	v_pk_add_f32 v[96:97], v[116:117], v[96:97] op_sel_hi:[0,1]
	v_pk_mul_f32 v[104:105], v[104:105], v[150:151] op_sel_hi:[1,0]
	v_mul_f32_e32 v118, v103, v103
	v_pk_fma_f32 v[96:97], v[102:103], v[102:103], v[96:97]
	v_pk_fma_f32 v[104:105], v[120:121], v[148:149], v[104:105] op_sel_hi:[1,0,1]
	v_pk_add_f32 v[96:97], v[118:119], v[96:97] op_sel_hi:[0,1]
	v_pk_mul_f32 v[106:107], v[106:107], v[150:151] op_sel_hi:[1,0]
	v_mul_f32_e32 v120, v105, v105
	v_pk_fma_f32 v[96:97], v[104:105], v[104:105], v[96:97]
	v_pk_fma_f32 v[106:107], v[122:123], v[148:149], v[106:107] op_sel_hi:[1,0,1]
	v_pk_add_f32 v[96:97], v[120:121], v[96:97] op_sel_hi:[0,1]
	v_pk_mul_f32 v[108:109], v[108:109], v[150:151] op_sel_hi:[1,0]
	v_mul_f32_e32 v122, v107, v107
	v_pk_fma_f32 v[96:97], v[106:107], v[106:107], v[96:97]
	v_pk_fma_f32 v[108:109], v[124:125], v[148:149], v[108:109] op_sel_hi:[1,0,1]
	v_pk_add_f32 v[96:97], v[122:123], v[96:97] op_sel_hi:[0,1]
	v_pk_mul_f32 v[110:111], v[110:111], v[150:151] op_sel_hi:[1,0]
	v_pk_fma_f32 v[96:97], v[108:109], v[108:109], v[96:97]
	v_mul_f32_e32 v98, v109, v109
	v_pk_fma_f32 v[110:111], v[126:127], v[148:149], v[110:111] op_sel_hi:[1,0,1]
	v_pk_add_f32 v[96:97], v[98:99], v[96:97] op_sel_hi:[0,1]
	v_pk_fma_f32 v[96:97], v[110:111], v[110:111], v[96:97]
	v_mul_f32_e32 v98, v111, v111
	v_pk_mul_f32 v[82:83], v[82:83], v[150:151] op_sel_hi:[1,0]
	v_pk_add_f32 v[118:119], v[98:99], v[96:97] op_sel_hi:[0,1]
	v_pk_fma_f32 v[96:97], v[66:67], v[148:149], v[82:83] op_sel_hi:[1,0,1]
	v_pk_mul_f32 v[66:67], v[80:81], v[150:151] op_sel_hi:[1,0]
	v_pk_fma_f32 v[98:99], v[64:65], v[148:149], v[66:67] op_sel_hi:[1,0,1]
	v_pk_fma_f32 v[64:65], v[98:99], v[98:99], v[118:119]
	v_mul_f32_e32 v66, v99, v99
	ds_read_b128 v[128:131], v219
	v_pk_add_f32 v[64:65], v[66:67], v[64:65] op_sel_hi:[0,1]
	v_pk_fma_f32 v[64:65], v[96:97], v[96:97], v[64:65]
	v_mul_f32_e32 v66, v97, v97
	v_pk_add_f32 v[64:65], v[66:67], v[64:65] op_sel_hi:[0,1]
	v_pk_mul_f32 v[66:67], v[86:87], v[150:151] op_sel_hi:[1,0]
	v_pk_mul_f32 v[50:51], v[50:51], v[150:151] op_sel_hi:[1,0]
	v_pk_fma_f32 v[80:81], v[70:71], v[148:149], v[66:67] op_sel_hi:[1,0,1]
	v_pk_mul_f32 v[66:67], v[84:85], v[150:151] op_sel_hi:[1,0]
	v_pk_mul_f32 v[18:19], v[18:19], v[150:151] op_sel_hi:[1,0]
	v_pk_fma_f32 v[82:83], v[68:69], v[148:149], v[66:67] op_sel_hi:[1,0,1]
	s_mov_b32 s0, 0x800000
	v_pk_fma_f32 v[64:65], v[82:83], v[82:83], v[64:65]
	v_mul_f32_e32 v66, v83, v83
	v_pk_add_f32 v[64:65], v[66:67], v[64:65] op_sel_hi:[0,1]
	v_pk_fma_f32 v[64:65], v[80:81], v[80:81], v[64:65]
	v_mul_f32_e32 v66, v81, v81
	v_pk_add_f32 v[64:65], v[66:67], v[64:65] op_sel_hi:[0,1]
	v_pk_mul_f32 v[66:67], v[90:91], v[150:151] op_sel_hi:[1,0]
	v_lshl_add_u64 v[140:141], s[68:69], 0, v[140:141]
	v_pk_fma_f32 v[74:75], v[74:75], v[148:149], v[66:67] op_sel_hi:[1,0,1]
	v_pk_mul_f32 v[66:67], v[88:89], v[150:151] op_sel_hi:[1,0]
	v_pk_fma_f32 v[72:73], v[72:73], v[148:149], v[66:67] op_sel_hi:[1,0,1]
	s_lshr_b32 s1, s100, 30
	s_add_i32 s1, s1, 3
	s_cmp_eq_u32 s74, s1
	v_pk_fma_f32 v[64:65], v[72:73], v[72:73], v[64:65]
	v_mul_f32_e32 v66, v73, v73
	v_pk_add_f32 v[64:65], v[66:67], v[64:65] op_sel_hi:[0,1]
	v_pk_fma_f32 v[64:65], v[74:75], v[74:75], v[64:65]
	v_mul_f32_e32 v66, v75, v75
	v_pk_add_f32 v[64:65], v[66:67], v[64:65] op_sel_hi:[0,1]
	v_pk_mul_f32 v[66:67], v[94:95], v[150:151] op_sel_hi:[1,0]
	s_waitcnt vmcnt(16) lgkmcnt(0)
	v_lshlrev_b32_e32 v116, 16, v160
	v_pk_fma_f32 v[68:69], v[78:79], v[148:149], v[66:67] op_sel_hi:[1,0,1]
	v_pk_mul_f32 v[66:67], v[92:93], v[150:151] op_sel_hi:[1,0]
	v_and_b32_e32 v117, 0xffff0000, v160
	v_pk_fma_f32 v[70:71], v[76:77], v[148:149], v[66:67] op_sel_hi:[1,0,1]
	s_nop 0
	v_pk_fma_f32 v[64:65], v[70:71], v[70:71], v[64:65]
	v_mul_f32_e32 v66, v71, v71
	v_pk_add_f32 v[64:65], v[66:67], v[64:65] op_sel_hi:[0,1]
	v_pk_fma_f32 v[64:65], v[68:69], v[68:69], v[64:65]
	v_mul_f32_e32 v66, v69, v69
	v_pk_add_f32 v[76:77], v[66:67], v[64:65] op_sel_hi:[0,1]
	v_pk_fma_f32 v[64:65], v[34:35], v[148:149], v[50:51] op_sel_hi:[1,0,1]
	v_pk_mul_f32 v[34:35], v[48:49], v[150:151] op_sel_hi:[1,0]
	s_nop 0
	v_pk_fma_f32 v[66:67], v[32:33], v[148:149], v[34:35] op_sel_hi:[1,0,1]
	s_nop 0
	v_pk_fma_f32 v[32:33], v[66:67], v[66:67], v[76:77]
	v_mul_f32_e32 v34, v67, v67
	v_pk_add_f32 v[32:33], v[34:35], v[32:33] op_sel_hi:[0,1]
	v_pk_fma_f32 v[32:33], v[64:65], v[64:65], v[32:33]
	v_mul_f32_e32 v34, v65, v65
	v_pk_add_f32 v[32:33], v[34:35], v[32:33] op_sel_hi:[0,1]
	v_pk_mul_f32 v[34:35], v[54:55], v[150:151] op_sel_hi:[1,0]
	s_nop 0
	v_pk_fma_f32 v[48:49], v[38:39], v[148:149], v[34:35] op_sel_hi:[1,0,1]
	v_pk_mul_f32 v[34:35], v[52:53], v[150:151] op_sel_hi:[1,0]
	s_nop 0
	v_pk_fma_f32 v[50:51], v[36:37], v[148:149], v[34:35] op_sel_hi:[1,0,1]
	s_nop 0
	v_pk_fma_f32 v[32:33], v[50:51], v[50:51], v[32:33]
	v_mul_f32_e32 v34, v51, v51
	v_pk_add_f32 v[32:33], v[34:35], v[32:33] op_sel_hi:[0,1]
	v_pk_fma_f32 v[32:33], v[48:49], v[48:49], v[32:33]
	v_mul_f32_e32 v34, v49, v49
	v_pk_add_f32 v[32:33], v[34:35], v[32:33] op_sel_hi:[0,1]
	v_pk_mul_f32 v[34:35], v[58:59], v[150:151] op_sel_hi:[1,0]
	s_nop 0
	v_pk_fma_f32 v[42:43], v[42:43], v[148:149], v[34:35] op_sel_hi:[1,0,1]
	v_pk_mul_f32 v[34:35], v[56:57], v[150:151] op_sel_hi:[1,0]
	s_nop 0
	v_pk_fma_f32 v[40:41], v[40:41], v[148:149], v[34:35] op_sel_hi:[1,0,1]
	s_nop 0
	v_pk_fma_f32 v[32:33], v[40:41], v[40:41], v[32:33]
	v_mul_f32_e32 v34, v41, v41
	v_pk_add_f32 v[32:33], v[34:35], v[32:33] op_sel_hi:[0,1]
	v_pk_fma_f32 v[32:33], v[42:43], v[42:43], v[32:33]
	v_mul_f32_e32 v34, v43, v43
	v_pk_add_f32 v[32:33], v[34:35], v[32:33] op_sel_hi:[0,1]
	v_pk_mul_f32 v[34:35], v[62:63], v[150:151] op_sel_hi:[1,0]
	s_nop 0
	v_pk_fma_f32 v[36:37], v[46:47], v[148:149], v[34:35] op_sel_hi:[1,0,1]
	v_pk_mul_f32 v[34:35], v[60:61], v[150:151] op_sel_hi:[1,0]
	s_nop 0
	v_pk_fma_f32 v[38:39], v[44:45], v[148:149], v[34:35] op_sel_hi:[1,0,1]
	s_nop 0
	v_pk_fma_f32 v[32:33], v[38:39], v[38:39], v[32:33]
	v_mul_f32_e32 v34, v39, v39
	v_pk_add_f32 v[32:33], v[34:35], v[32:33] op_sel_hi:[0,1]
	v_pk_fma_f32 v[32:33], v[36:37], v[36:37], v[32:33]
	v_mul_f32_e32 v34, v37, v37
	v_pk_add_f32 v[44:45], v[34:35], v[32:33] op_sel_hi:[0,1]
	v_pk_fma_f32 v[32:33], v[2:3], v[148:149], v[18:19] op_sel_hi:[1,0,1]
	v_pk_mul_f32 v[2:3], v[16:17], v[150:151] op_sel_hi:[1,0]
	s_nop 0
	v_pk_fma_f32 v[34:35], v[0:1], v[148:149], v[2:3] op_sel_hi:[1,0,1]
	s_nop 0
	v_pk_fma_f32 v[0:1], v[34:35], v[34:35], v[44:45]
	v_mul_f32_e32 v2, v35, v35
	v_pk_add_f32 v[0:1], v[2:3], v[0:1] op_sel_hi:[0,1]
	v_pk_fma_f32 v[0:1], v[32:33], v[32:33], v[0:1]
	v_mul_f32_e32 v2, v33, v33
	v_pk_add_f32 v[0:1], v[2:3], v[0:1] op_sel_hi:[0,1]
	v_pk_mul_f32 v[2:3], v[22:23], v[150:151] op_sel_hi:[1,0]
	v_lshlrev_b32_e32 v22, 16, v165
	v_pk_fma_f32 v[16:17], v[6:7], v[148:149], v[2:3] op_sel_hi:[1,0,1]
	v_pk_mul_f32 v[2:3], v[20:21], v[150:151] op_sel_hi:[1,0]
	v_and_b32_e32 v23, 0xffff0000, v165
	v_pk_fma_f32 v[18:19], v[4:5], v[148:149], v[2:3] op_sel_hi:[1,0,1]
	s_nop 0
	v_pk_fma_f32 v[0:1], v[18:19], v[18:19], v[0:1]
	v_mul_f32_e32 v2, v19, v19
	v_pk_add_f32 v[0:1], v[2:3], v[0:1] op_sel_hi:[0,1]
	v_pk_fma_f32 v[0:1], v[16:17], v[16:17], v[0:1]
	v_mul_f32_e32 v2, v17, v17
	v_pk_add_f32 v[0:1], v[2:3], v[0:1] op_sel_hi:[0,1]
	v_pk_mul_f32 v[2:3], v[26:27], v[150:151] op_sel_hi:[1,0]
	s_nop 0
	v_pk_fma_f32 v[10:11], v[10:11], v[148:149], v[2:3] op_sel_hi:[1,0,1]
	v_pk_mul_f32 v[2:3], v[24:25], v[150:151] op_sel_hi:[1,0]
	s_nop 0
	v_pk_fma_f32 v[8:9], v[8:9], v[148:149], v[2:3] op_sel_hi:[1,0,1]
	s_nop 0
	v_pk_fma_f32 v[0:1], v[8:9], v[8:9], v[0:1]
	v_mul_f32_e32 v2, v9, v9
	v_pk_add_f32 v[0:1], v[2:3], v[0:1] op_sel_hi:[0,1]
	v_pk_fma_f32 v[0:1], v[10:11], v[10:11], v[0:1]
	v_mul_f32_e32 v2, v11, v11
	v_pk_add_f32 v[4:5], v[2:3], v[0:1] op_sel_hi:[0,1]
	v_pk_mul_f32 v[2:3], v[28:29], v[150:151] op_sel_hi:[1,0]
	v_pk_mul_f32 v[0:1], v[30:31], v[150:151] op_sel_hi:[1,0]
	v_pk_fma_f32 v[2:3], v[12:13], v[148:149], v[2:3] op_sel_hi:[1,0,1]
	v_pk_fma_f32 v[0:1], v[14:15], v[148:149], v[0:1] op_sel_hi:[1,0,1]
	v_pk_fma_f32 v[4:5], v[2:3], v[2:3], v[4:5]
	v_mul_f32_e32 v6, v3, v3
	v_pk_add_f32 v[4:5], v[6:7], v[4:5] op_sel_hi:[0,1]
	v_pk_fma_f32 v[4:5], v[0:1], v[0:1], v[4:5]
	v_mul_f32_e32 v6, v1, v1
	v_pk_add_f32 v[4:5], v[6:7], v[4:5] op_sel_hi:[0,1]
	v_mov_b32_e32 v5, v4
	s_nop 1
	v_permlane32_swap_b32_e32 v4, v5
	v_add_f32_e32 v4, v4, v5
	v_fmamk_f32 v4, v4, 0x3c000000, v232
	v_mul_f32_e32 v5, 0x4b800000, v4
	v_cmp_gt_f32_e32 vcc, s0, v4
	v_lshlrev_b32_e32 v12, 16, v161
	v_and_b32_e32 v13, 0xffff0000, v161
	v_cndmask_b32_e32 v4, v4, v5, vcc
	v_rsq_f32_e32 v6, v4
	v_lshl_add_u64 v[4:5], v[140:141], 0, v[136:137]
	v_lshlrev_b32_e32 v138, 3, v210
	v_mov_b32_e32 v139, 0
	v_lshl_add_u64 v[142:143], v[138:139], 0, v[4:5]
	v_mul_f32_e32 v7, 0x45800000, v6
	v_cndmask_b32_e32 v6, v6, v7, vcc
	v_mul_f32_e32 v6, 0x3f077f5a, v6
	v_pk_mul_f32 v[14:15], v[112:113], v[6:7] op_sel_hi:[1,0]
	v_pk_mul_f32 v[20:21], v[114:115], v[6:7] op_sel_hi:[1,0]
	v_pk_mul_f32 v[14:15], v[128:129], v[14:15]
	v_pk_mul_f32 v[20:21], v[130:131], v[20:21]
	v_pk_mul_f32 v[14:15], v[14:15], v[116:117]
	v_pk_mul_f32 v[12:13], v[20:21], v[12:13]
	v_cvt_pk_bf16_f32 v144, v14, v15
	v_cvt_pk_bf16_f32 v145, v12, v13
	ds_read_b128 v[12:15], v219 offset:32
	v_pk_mul_f32 v[20:21], v[100:101], v[6:7] op_sel_hi:[1,0]
	v_pk_mul_f32 v[24:25], v[104:105], v[6:7] op_sel_hi:[1,0]
	v_pk_mul_f32 v[26:27], v[106:107], v[6:7] op_sel_hi:[1,0]
	v_pk_mul_f32 v[28:29], v[110:111], v[6:7] op_sel_hi:[1,0]
	v_pk_mul_f32 v[30:31], v[98:99], v[6:7] op_sel_hi:[1,0]
	v_pk_mul_f32 v[44:45], v[96:97], v[6:7] op_sel_hi:[1,0]
	v_pk_mul_f32 v[32:33], v[32:33], v[6:7] op_sel_hi:[1,0]
	v_pk_mul_f32 v[18:19], v[18:19], v[6:7] op_sel_hi:[1,0]
	v_pk_mul_f32 v[16:17], v[16:17], v[6:7] op_sel_hi:[1,0]
	v_pk_mul_f32 v[8:9], v[8:9], v[6:7] op_sel_hi:[1,0]
	v_pk_mul_f32 v[10:11], v[10:11], v[6:7] op_sel_hi:[1,0]
	v_pk_mul_f32 v[2:3], v[2:3], v[6:7] op_sel_hi:[1,0]
	v_pk_mul_f32 v[0:1], v[0:1], v[6:7] op_sel_hi:[1,0]
	s_waitcnt lgkmcnt(0)
	v_pk_mul_f32 v[12:13], v[12:13], v[20:21]
	v_lshlrev_b32_e32 v20, 16, v162
	v_and_b32_e32 v21, 0xffff0000, v162
	v_pk_mul_f32 v[12:13], v[12:13], v[20:21]
	v_pk_mul_f32 v[20:21], v[102:103], v[6:7] op_sel_hi:[1,0]
	v_cvt_pk_bf16_f32 v146, v12, v13
	v_pk_mul_f32 v[14:15], v[14:15], v[20:21]
	v_lshlrev_b32_e32 v20, 16, v163
	v_and_b32_e32 v21, 0xffff0000, v163
	v_pk_mul_f32 v[14:15], v[14:15], v[20:21]
	v_lshlrev_b32_e32 v20, 16, v164
	v_cvt_pk_bf16_f32 v147, v14, v15
	s_nop 1
	v_permlane32_swap_b32_e32 v144, v146
	v_permlane32_swap_b32_e32 v145, v147
	global_store_dwordx4 v[142:143], v[144:147], off
	ds_read_b128 v[12:15], v219 offset:64
	v_and_b32_e32 v21, 0xffff0000, v164
	s_waitcnt lgkmcnt(0)
	v_pk_mul_f32 v[12:13], v[12:13], v[24:25]
	v_pk_mul_f32 v[14:15], v[14:15], v[26:27]
	v_pk_mul_f32 v[12:13], v[12:13], v[20:21]
	v_pk_mul_f32 v[14:15], v[14:15], v[22:23]
	v_cvt_pk_bf16_f32 v144, v12, v13
	v_cvt_pk_bf16_f32 v145, v14, v15
	ds_read_b128 v[12:15], v219 offset:96
	s_nop 0
	v_pk_mul_f32 v[26:27], v[108:109], v[6:7] op_sel_hi:[1,0]
	v_lshlrev_b32_e32 v22, 16, v166
	v_and_b32_e32 v23, 0xffff0000, v166
	v_lshlrev_b32_e32 v24, 16, v167
	v_and_b32_e32 v25, 0xffff0000, v167
	s_waitcnt lgkmcnt(0)
	v_pk_mul_f32 v[12:13], v[12:13], v[26:27]
	v_pk_mul_f32 v[14:15], v[14:15], v[28:29]
	v_pk_mul_f32 v[12:13], v[12:13], v[22:23]
	v_pk_mul_f32 v[14:15], v[14:15], v[24:25]
	v_cvt_pk_bf16_f32 v146, v12, v13
	v_cvt_pk_bf16_f32 v147, v14, v15
	s_nop 1
	v_permlane32_swap_b32_e32 v144, v146
	v_permlane32_swap_b32_e32 v145, v147
	global_store_dwordx4 v[142:143], v[144:147], off offset:32
	ds_read_b128 v[12:15], v219 offset:128
	s_nop 0
	v_lshlrev_b32_e32 v28, 16, v168
	v_and_b32_e32 v29, 0xffff0000, v168
	v_lshlrev_b32_e32 v20, 16, v169
	v_and_b32_e32 v21, 0xffff0000, v169
	s_waitcnt lgkmcnt(0)
	v_pk_mul_f32 v[12:13], v[30:31], v[12:13]
	v_pk_mul_f32 v[14:15], v[44:45], v[14:15]
	v_pk_mul_f32 v[12:13], v[12:13], v[28:29]
	v_pk_mul_f32 v[14:15], v[14:15], v[20:21]
	v_cvt_pk_bf16_f32 v144, v12, v13
	v_cvt_pk_bf16_f32 v145, v14, v15
	ds_read_b128 v[12:15], v219 offset:160
	v_pk_mul_f32 v[28:29], v[82:83], v[6:7] op_sel_hi:[1,0]
	v_pk_mul_f32 v[30:31], v[80:81], v[6:7] op_sel_hi:[1,0]
	v_lshlrev_b32_e32 v20, 16, v170
	v_and_b32_e32 v21, 0xffff0000, v170
	v_lshlrev_b32_e32 v22, 16, v171
	v_and_b32_e32 v23, 0xffff0000, v171
	v_pk_mul_f32 v[44:45], v[64:65], v[6:7] op_sel_hi:[1,0]
	s_waitcnt lgkmcnt(0)
	v_pk_mul_f32 v[12:13], v[28:29], v[12:13]
	v_pk_mul_f32 v[14:15], v[30:31], v[14:15]
	v_pk_mul_f32 v[12:13], v[12:13], v[20:21]
	v_pk_mul_f32 v[14:15], v[14:15], v[22:23]
	v_cvt_pk_bf16_f32 v146, v12, v13
	v_cvt_pk_bf16_f32 v147, v14, v15
	s_nop 1
	v_permlane32_swap_b32_e32 v144, v146
	v_permlane32_swap_b32_e32 v145, v147
	global_store_dwordx4 v[142:143], v[144:147], off offset:64
	ds_read_b128 v[12:15], v219 offset:192
	v_lshlrev_b32_e32 v20, 16, v172
	v_and_b32_e32 v21, 0xffff0000, v172
	v_lshlrev_b32_e32 v22, 16, v173
	v_and_b32_e32 v23, 0xffff0000, v173
	v_pk_mul_f32 v[24:25], v[72:73], v[6:7] op_sel_hi:[1,0]
	v_pk_mul_f32 v[28:29], v[74:75], v[6:7] op_sel_hi:[1,0]
	v_pk_mul_f32 v[30:31], v[66:67], v[6:7] op_sel_hi:[1,0]
	s_waitcnt lgkmcnt(0)
	v_pk_mul_f32 v[12:13], v[24:25], v[12:13]
	v_pk_mul_f32 v[14:15], v[28:29], v[14:15]
	v_pk_mul_f32 v[12:13], v[12:13], v[20:21]
	v_pk_mul_f32 v[14:15], v[14:15], v[22:23]
	v_cvt_pk_bf16_f32 v144, v12, v13
	v_cvt_pk_bf16_f32 v145, v14, v15
	ds_read_b128 v[12:15], v219 offset:224
	s_nop 0
	v_lshlrev_b32_e32 v22, 16, v174
	v_and_b32_e32 v23, 0xffff0000, v174
	v_lshlrev_b32_e32 v24, 16, v175
	v_and_b32_e32 v25, 0xffff0000, v175
	v_pk_mul_f32 v[26:27], v[70:71], v[6:7] op_sel_hi:[1,0]
	v_pk_mul_f32 v[28:29], v[68:69], v[6:7] op_sel_hi:[1,0]
	s_waitcnt lgkmcnt(0)
	v_pk_mul_f32 v[12:13], v[26:27], v[12:13]
	v_pk_mul_f32 v[14:15], v[28:29], v[14:15]
	v_pk_mul_f32 v[12:13], v[12:13], v[22:23]
	v_pk_mul_f32 v[14:15], v[14:15], v[24:25]
	v_cvt_pk_bf16_f32 v146, v12, v13
	v_cvt_pk_bf16_f32 v147, v14, v15
	s_nop 1
	v_permlane32_swap_b32_e32 v144, v146
	v_permlane32_swap_b32_e32 v145, v147
	global_store_dwordx4 v[142:143], v[144:147], off offset:96
	ds_read_b128 v[12:15], v219 offset:256
	s_nop 0
	v_lshlrev_b32_e32 v28, 16, v202
	v_and_b32_e32 v29, 0xffff0000, v202
	v_lshlrev_b32_e32 v20, 16, v203
	v_and_b32_e32 v21, 0xffff0000, v203
	s_waitcnt lgkmcnt(0)
	v_pk_mul_f32 v[12:13], v[30:31], v[12:13]
	v_pk_mul_f32 v[14:15], v[44:45], v[14:15]
	v_pk_mul_f32 v[12:13], v[12:13], v[28:29]
	v_pk_mul_f32 v[14:15], v[14:15], v[20:21]
	v_cvt_pk_bf16_f32 v144, v12, v13
	v_cvt_pk_bf16_f32 v145, v14, v15
	ds_read_b128 v[12:15], v219 offset:288
	v_pk_mul_f32 v[28:29], v[50:51], v[6:7] op_sel_hi:[1,0]
	v_pk_mul_f32 v[30:31], v[48:49], v[6:7] op_sel_hi:[1,0]
	v_lshlrev_b32_e32 v20, 16, v204
	v_and_b32_e32 v21, 0xffff0000, v204
	v_lshlrev_b32_e32 v22, 16, v205
	v_and_b32_e32 v23, 0xffff0000, v205
	s_waitcnt lgkmcnt(0)
	v_pk_mul_f32 v[12:13], v[28:29], v[12:13]
	v_pk_mul_f32 v[14:15], v[30:31], v[14:15]
	v_pk_mul_f32 v[12:13], v[12:13], v[20:21]
	v_pk_mul_f32 v[14:15], v[14:15], v[22:23]
	v_cvt_pk_bf16_f32 v146, v12, v13
	v_cvt_pk_bf16_f32 v147, v14, v15
	s_nop 1
	v_permlane32_swap_b32_e32 v144, v146
	v_permlane32_swap_b32_e32 v145, v147
	global_store_dwordx4 v[142:143], v[144:147], off offset:128
	ds_read_b128 v[12:15], v219 offset:320
	v_lshlrev_b32_e32 v20, 16, v244
	v_and_b32_e32 v21, 0xffff0000, v244
	v_lshlrev_b32_e32 v22, 16, v245
	v_and_b32_e32 v23, 0xffff0000, v245
	v_pk_mul_f32 v[24:25], v[40:41], v[6:7] op_sel_hi:[1,0]
	v_pk_mul_f32 v[28:29], v[42:43], v[6:7] op_sel_hi:[1,0]
	v_pk_mul_f32 v[30:31], v[34:35], v[6:7] op_sel_hi:[1,0]
	s_waitcnt lgkmcnt(0)
	v_pk_mul_f32 v[12:13], v[24:25], v[12:13]
	v_pk_mul_f32 v[14:15], v[28:29], v[14:15]
	v_pk_mul_f32 v[12:13], v[12:13], v[20:21]
	v_pk_mul_f32 v[14:15], v[14:15], v[22:23]
	v_cvt_pk_bf16_f32 v144, v12, v13
	v_cvt_pk_bf16_f32 v145, v14, v15
	ds_read_b128 v[12:15], v219 offset:352
	s_nop 0
	v_lshlrev_b32_e32 v22, 16, v246
	v_and_b32_e32 v23, 0xffff0000, v246
	v_lshlrev_b32_e32 v24, 16, v247
	v_and_b32_e32 v25, 0xffff0000, v247
	v_pk_mul_f32 v[26:27], v[38:39], v[6:7] op_sel_hi:[1,0]
	v_pk_mul_f32 v[28:29], v[36:37], v[6:7] op_sel_hi:[1,0]
	s_waitcnt lgkmcnt(0)
	v_pk_mul_f32 v[12:13], v[26:27], v[12:13]
	v_pk_mul_f32 v[14:15], v[28:29], v[14:15]
	v_pk_mul_f32 v[12:13], v[12:13], v[22:23]
	v_pk_mul_f32 v[14:15], v[14:15], v[24:25]
	v_cvt_pk_bf16_f32 v146, v12, v13
	v_cvt_pk_bf16_f32 v147, v14, v15
	s_nop 1
	v_permlane32_swap_b32_e32 v144, v146
	v_permlane32_swap_b32_e32 v145, v147
	global_store_dwordx4 v[142:143], v[144:147], off offset:160
	ds_read_b128 v[12:15], v219 offset:384
	s_nop 0
	v_lshlrev_b32_e32 v28, 16, v248
	v_and_b32_e32 v29, 0xffff0000, v248
	v_lshlrev_b32_e32 v20, 16, v249
	v_and_b32_e32 v21, 0xffff0000, v249
	s_waitcnt lgkmcnt(0)
	v_pk_mul_f32 v[12:13], v[30:31], v[12:13]
	v_pk_mul_f32 v[14:15], v[32:33], v[14:15]
	v_pk_mul_f32 v[12:13], v[12:13], v[28:29]
	v_pk_mul_f32 v[14:15], v[14:15], v[20:21]
	v_cvt_pk_bf16_f32 v144, v12, v13
	v_cvt_pk_bf16_f32 v145, v14, v15
	ds_read_b128 v[12:15], v219 offset:416
	v_lshlrev_b32_e32 v20, 16, v250
	v_and_b32_e32 v21, 0xffff0000, v250
	v_lshlrev_b32_e32 v22, 16, v251
	v_and_b32_e32 v23, 0xffff0000, v251
	s_waitcnt lgkmcnt(0)
	v_pk_mul_f32 v[12:13], v[18:19], v[12:13]
	v_pk_mul_f32 v[14:15], v[16:17], v[14:15]
	v_pk_mul_f32 v[12:13], v[12:13], v[20:21]
	v_pk_mul_f32 v[14:15], v[14:15], v[22:23]
	v_cvt_pk_bf16_f32 v146, v12, v13
	v_cvt_pk_bf16_f32 v147, v14, v15
	s_nop 1
	v_permlane32_swap_b32_e32 v144, v146
	v_permlane32_swap_b32_e32 v145, v147
	global_store_dwordx4 v[142:143], v[144:147], off offset:192
	ds_read_b128 v[12:15], v219 offset:448
	v_lshlrev_b32_e32 v16, 16, v252
	v_and_b32_e32 v17, 0xffff0000, v252
	v_lshlrev_b32_e32 v18, 16, v253
	v_and_b32_e32 v19, 0xffff0000, v253
	s_waitcnt lgkmcnt(0)
	v_pk_mul_f32 v[8:9], v[8:9], v[12:13]
	v_pk_mul_f32 v[10:11], v[10:11], v[14:15]
	v_pk_mul_f32 v[8:9], v[8:9], v[16:17]
	v_pk_mul_f32 v[10:11], v[10:11], v[18:19]
	v_cvt_pk_bf16_f32 v144, v8, v9
	v_cvt_pk_bf16_f32 v145, v10, v11
	ds_read_b128 v[8:11], v219 offset:480
	v_lshlrev_b32_e32 v12, 16, v254
	v_and_b32_e32 v13, 0xffff0000, v254
	v_lshlrev_b32_e32 v14, 16, v255
	v_and_b32_e32 v15, 0xffff0000, v255
	s_waitcnt lgkmcnt(0)
	v_pk_mul_f32 v[2:3], v[2:3], v[8:9]
	v_pk_mul_f32 v[0:1], v[0:1], v[10:11]
	v_pk_mul_f32 v[2:3], v[2:3], v[12:13]
	v_pk_mul_f32 v[0:1], v[0:1], v[14:15]
	v_cvt_pk_bf16_f32 v146, v2, v3
	v_cvt_pk_bf16_f32 v147, v0, v1
	s_nop 1
	v_permlane32_swap_b32_e32 v144, v146
	v_permlane32_swap_b32_e32 v145, v147
	global_store_dwordx4 v[142:143], v[144:147], off offset:224
	s_cbranch_scc1 .LBB0_735
	s_branch .LBB0_736
